# gdn gate loads batched on top of ssq/nt/phase-final batching
# baseline (speedup 1.0000x reference)
; #define TIDX opaque_tid()
; #define AIN(i) ((const float*)(__attribute__((address_space(1))) const float*)karg_u64(8 * (i)))
; __device__ __forceinline__ float sigmoidf_(float x) { return __builtin_amdgcn_rcpf(1.f + __expf(-x)); }
; __device__ __forceinline__ float ldnt(const float* p) { return __builtin_nontemporal_load(p); }
; __device__ __forceinline__ void lds_barrier() { asm volatile("s_waitcnt lgkmcnt(0)\n\ts_barrier" ::: "memory"); }
; #define WSP(T, off) ((T*)(__attribute__((address_space(1))) T*)(launder_ws(AWS, (off))))
; __device__ __forceinline__ void gdn_chunk(const Args& a, int l, int ci, unsigned char* lds) {
;     const int bh = ci >> 6, n = ci & 63, b = bh / 5, h = bh % 5, tb = b * SEQ + n * 64, s0 = n * 64;
;     float* qf = (float*)lds; float* kf = qf + 64 * 128; float* vf = kf + 64 * 128;
;     bf16_t* qb = (bf16_t*)(vf + 64 * 128); bf16_t* kb = qb + 64 * 136;
;     float* gcs = (float*)(kb + 64 * 136); float* bts = gcs + 64; float* rq = bts + 64; float* rk = rq + 64;
;     float* Am = qf;
;     const int tid = TIDX, w = tid >> 6, lane = tid & 63, fr = lane & 15, fq = lane >> 4;
;     const float* P = WSP(const float, WS_P);
;     lds_barrier();
;     if (w == 0) {
;         const int t = tb + lane;
;         const float av = ldnt(P + ((size_t)t * INP + C_GA + h)) + AIN(16)[l * 5 + h];
;         const float ev = __expf(av);
;         const float sp = av > 20.f ? av : (ev < 0.0625f ? ev * (1.f - ev * (0.5f - ev * (0.33333334f - 0.25f * ev))) : __logf(1.f + ev));
;         float g = -__expf(AIN(15)[l * 5 + h]) * sp;
; #pragma unroll
;         for (int o = 1; o < 64; o <<= 1) { const float x = __shfl_up(g, o); if (lane >= o) g += x; }
;         gcs[lane] = g;
;         bts[lane] = sigmoidf_(ldnt(P + ((size_t)t * INP + C_GB + h)));
.LBB0_634:
	s_andn2_b64 vcc, exec, s[2:3]
	s_cbranch_vccnz .LBB0_601
	s_ashr_i32 s2, s50, 6
	s_mul_hi_i32 s3, s2, 0x66666667
	s_lshr_b32 s13, s3, 31
	s_ashr_i32 s3, s3, 1
	s_add_i32 s3, s3, s13
	s_mul_i32 s13, s3, 5
	s_sub_i32 s16, s2, s13
	s_lshl_b32 s2, s50, 6
	s_lshl_b32 s13, s3, 12
	s_and_b32 s14, s2, 0xfc0
	v_mov_b32_e32 v8, v224
	s_mov_b64 s[2:3], s[0:1]
	s_load_dwordx2 s[2:3], s[2:3], 0xd0
	s_mov_b64 s[18:19], 0xec18000
	s_or_b32 s13, s13, s14
	s_waitcnt lgkmcnt(0)
	s_barrier
	s_waitcnt lgkmcnt(0)
	s_add_u32 s2, s2, s18
	v_and_b32_e32 v9, 63, v8
	s_addc_u32 s3, s3, s19
	v_cmp_gt_u32_e32 vcc, 64, v8
	s_and_saveexec_b64 s[18:19], vcc
	s_cbranch_execz .LBB0_643
	v_or_b32_e32 v2, s13, v8
	v_mov_b64_e32 v[0:1], s[2:3]
	s_ashr_i32 s17, s16, 31
	v_mad_i64_i32 v[0:1], s[20:21], v2, s95, v[0:1]
	v_lshl_add_u64 v[0:1], s[16:17], 2, v[0:1]
	v_add_co_u32_e32 v2, vcc, 0x7000, v0
	s_mov_b64 s[20:21], s[0:1]
	s_nop 0
	v_addc_co_u32_e32 v3, vcc, 0, v1, vcc
	global_load_dword v2, v[2:3], off offset:1096 nt
	global_load_dword v240, v[2:3], off offset:1116 nt
	s_load_dwordx2 s[22:23], s[20:21], 0x80
	s_load_dwordx2 s[100:101], s[20:21], 0x78
	v_readlane_b32 s20, v255, 28
	s_mul_i32 s15, s20, 5
	v_readlane_b32 s21, v255, 29
	s_add_i32 s20, s16, s15
	s_ashr_i32 s21, s20, 31
	s_lshl_b64 s[20:21], s[20:21], 2
	s_waitcnt lgkmcnt(0)
	s_add_u32 s22, s22, s20
	s_addc_u32 s23, s23, s21
	global_load_dword v3, v215, s[22:23]
	s_add_u32 s100, s100, s20
	s_addc_u32 s101, s101, s21
	global_load_dword v241, v215, s[100:101]
	s_mov_b32 s15, 0x41a00000
	s_waitcnt vmcnt(0)
	v_add_f32_e32 v2, v2, v3
	v_cmp_nlt_f32_e32 vcc, s15, v2
	s_and_saveexec_b64 s[22:23], vcc
	s_cbranch_execz .LBB0_642
	v_mul_f32_e32 v2, 0x3fb8aa3b, v2
	v_exp_f32_e32 v3, v2
	s_mov_b32 s15, 0x3d800000
	v_cmp_ngt_f32_e32 vcc, s15, v3
	s_and_saveexec_b64 s[24:25], vcc
	s_xor_b64 s[24:25], exec, s[24:25]
	s_cbranch_execz .LBB0_639
	v_add_f32_e32 v2, 1.0, v3
	v_cmp_gt_f32_e32 vcc, s96, v2
	s_mov_b32 s15, 0x3f317217
	s_nop 0
	v_cndmask_b32_e64 v3, 0, 32, vcc
	v_ldexp_f32 v2, v2, v3
	v_log_f32_e32 v2, v2
	s_nop 0
	v_mul_f32_e32 v3, 0x3f317217, v2
	v_fma_f32 v3, v2, s15, -v3
	v_fmac_f32_e32 v3, 0x3377d1cf, v2
	s_mov_b32 s15, 0x7f800000
	v_fmac_f32_e32 v3, 0x3f317217, v2
	v_cmp_lt_f32_e64 s[40:41], |v2|, s15
	s_nop 1
	v_cndmask_b32_e64 v2, v2, v3, s[40:41]
	v_cndmask_b32_e32 v3, 0, v237, vcc
	v_sub_f32_e32 v2, v2, v3

; #define AIN(i) ((const float*)(__attribute__((address_space(1))) const float*)karg_u64(8 * (i)))
; __device__ __forceinline__ float sigmoidf_(float x) { return __builtin_amdgcn_rcpf(1.f + __expf(-x)); }
; __device__ __forceinline__ float ldnt(const float* p) { return __builtin_nontemporal_load(p); }
; __device__ __forceinline__ void gdn_chunk(const Args& a, int l, int ci, unsigned char* lds) {
;     ...
;         float g = -__expf(AIN(15)[l * 5 + h]) * sp;
; #pragma unroll
;         for (int o = 1; o < 64; o <<= 1) { const float x = __shfl_up(g, o); if (lane >= o) g += x; }
;         gcs[lane] = g;
;         bts[lane] = sigmoidf_(ldnt(P + ((size_t)t * INP + C_GB + h)));
.LBB0_642:
	s_or_b64 exec, exec, s[22:23]
	s_mov_b64 s[22:23], s[0:1]
	s_load_dwordx2 s[22:23], s[22:23], 0x78
	v_and_b32_e32 v5, 64, v226
	v_add_u32_e32 v6, -1, v226
	v_cmp_lt_i32_e32 vcc, v6, v5
	s_waitcnt lgkmcnt(0)
	s_add_u32 s20, s22, s20
	s_addc_u32 s21, s23, s21
	v_mov_b32_e32 v3, v241
	v_cndmask_b32_e32 v6, v6, v226, vcc
	v_lshlrev_b32_e32 v6, 2, v6
	v_cmp_eq_u32_e32 vcc, 0, v9
	s_waitcnt vmcnt(0)
	v_mul_f32_e32 v3, 0x3fb8aa3b, v3
	v_exp_f32_e32 v3, v3
	s_nop 0
	v_mul_f32_e64 v4, v2, -v3
	ds_bpermute_b32 v6, v6, v4
	s_waitcnt lgkmcnt(0)
	v_fma_f32 v2, v2, -v3, v6
	v_add_u32_e32 v3, -2, v226
	v_cndmask_b32_e32 v2, v2, v4, vcc
	v_cmp_lt_i32_e32 vcc, v3, v5
	s_nop 1
	v_cndmask_b32_e32 v3, v3, v226, vcc
	v_lshlrev_b32_e32 v3, 2, v3
	ds_bpermute_b32 v3, v3, v2
	v_cmp_gt_u32_e32 vcc, 2, v9
	s_waitcnt lgkmcnt(0)
	v_add_f32_e32 v3, v2, v3
	v_cndmask_b32_e32 v2, v3, v2, vcc
	v_add_u32_e32 v3, -4, v226
	v_cmp_lt_i32_e32 vcc, v3, v5
	s_nop 1
	v_cndmask_b32_e32 v3, v3, v226, vcc
	v_lshlrev_b32_e32 v3, 2, v3
	ds_bpermute_b32 v3, v3, v2
	v_cmp_gt_u32_e32 vcc, 4, v9
	s_waitcnt lgkmcnt(0)
	v_add_f32_e32 v3, v2, v3
	v_cndmask_b32_e32 v2, v3, v2, vcc
	v_add_u32_e32 v3, -8, v226
	v_cmp_lt_i32_e32 vcc, v3, v5
	s_nop 1
	v_cndmask_b32_e32 v3, v3, v226, vcc
	v_lshlrev_b32_e32 v3, 2, v3
	ds_bpermute_b32 v3, v3, v2
	v_cmp_gt_u32_e32 vcc, 8, v9
	s_waitcnt lgkmcnt(0)
	v_add_f32_e32 v3, v2, v3
	v_cndmask_b32_e32 v2, v3, v2, vcc
	v_add_u32_e32 v3, -16, v226
	v_cmp_lt_i32_e32 vcc, v3, v5
	s_nop 1
	v_cndmask_b32_e32 v3, v3, v226, vcc
	v_lshlrev_b32_e32 v3, 2, v3
	ds_bpermute_b32 v3, v3, v2
	v_cmp_gt_u32_e32 vcc, 16, v9
	s_waitcnt lgkmcnt(0)
	v_add_f32_e32 v3, v2, v3
	v_cndmask_b32_e32 v2, v3, v2, vcc
	v_subrev_u32_e32 v3, 32, v226
	v_cmp_lt_i32_e32 vcc, v3, v5
	s_nop 1
	v_cndmask_b32_e32 v3, v3, v226, vcc
	v_lshlrev_b32_e32 v3, 2, v3
	ds_bpermute_b32 v3, v3, v2
	v_cmp_gt_u32_e32 vcc, 32, v9
	s_waitcnt lgkmcnt(0)
	v_add_f32_e32 v3, v2, v3
	v_cndmask_b32_e32 v2, v3, v2, vcc
	v_add_co_u32_e32 v0, vcc, 0x7000, v0
	v_lshl_add_u32 v3, v9, 2, 0
	s_nop 0
	v_addc_co_u32_e32 v1, vcc, 0, v1, vcc
	v_mov_b32_e32 v0, v240
	v_add_u32_e32 v4, 0x20800, v3
	v_add_u32_e32 v1, 0x20900, v3
	ds_write_b32 v4, v2
	s_waitcnt vmcnt(0)
	v_mul_f32_e32 v0, 0xbfb8aa3b, v0
	v_exp_f32_e32 v0, v0
	s_nop 0
	v_add_f32_e32 v0, 1.0, v0
	v_rcp_f32_e32 v0, v0
	ds_write_b32 v1, v0
